# speedup vs baseline: 1.0128x; 1.0063x over previous
; template <int EPI>
; __device__ __forceinline__ void gemm_stream(const bf16_t* __restrict__ A, const bf16_t* __restrict__ Bt, int K, const TileWalk& tw,
;                                             const EpiArgs& ea, unsigned char* smem) {
;     ...
;             if (EPI == EPI_RESID && seg && (kt == 8 || kt == 12)) {
; #pragma unroll
;                 for (int m = 0; m < 8; ++m) {
;                     const int tok = mt * 256 + wr * 128 + m * 16 + (lane & 15);
;                     const float rb = rsqrtf(ea.sq_b[tok] * (1.f / 256) + EPS);
;                     const float f = (kt == 8) ? rsqrtf(ea.sq_c[tok] * (1.f / 512) + EPS) / rb : rb;
; #pragma unroll
;                     for (int n = 0; n < 4; ++n) acc[m][n] *= f;
;                 }
;             }
.LBB0_306:
	s_andn2_b64 vcc, exec, s[4:5]
	s_cbranch_vccnz .LBB0_324
	global_load_dword v0, v[198:199], off
	global_load_dword v2, v[198:199], off offset:64
	global_load_dword v132, v[198:199], off offset:128
	global_load_dword v134, v[198:199], off offset:192
	global_load_dword v138, v[198:199], off offset:256
	global_load_dword v140, v[198:199], off offset:320
	global_load_dword v142, v[198:199], off offset:384
	global_load_dword v136, v[198:199], off offset:448
	s_cmp_lg_u32 s39, 8
	s_cbranch_scc1 .Lmy_rs_a
	global_load_dword v144, v[200:201], off
	global_load_dword v145, v[200:201], off offset:64
	global_load_dword v146, v[200:201], off offset:128
	global_load_dword v147, v[200:201], off offset:192
	global_load_dword v148, v[200:201], off offset:256
	global_load_dword v149, v[200:201], off offset:320
	global_load_dword v150, v[200:201], off offset:384
	global_load_dword v151, v[200:201], off offset:448
.Lmy_rs_a:
	s_waitcnt vmcnt(0)
	v_fmamk_f32 v0, v0, 0x3b800000, v188
	v_mul_f32_e32 v3, 0x4b800000, v0
	v_cmp_gt_f32_e64 s[6:7], s74, v0
	s_nop 1
	v_cndmask_b32_e64 v0, v0, v3, s[6:7]
	v_rsq_f32_e32 v0, v0
	s_nop 0
	v_mul_f32_e32 v3, 0x45800000, v0
	v_cndmask_b32_e64 v0, v0, v3, s[6:7]
	v_fmamk_f32 v2, v2, 0x3b800000, v188
	v_mul_f32_e32 v3, 0x4b800000, v2
	v_cmp_gt_f32_e64 s[6:7], s74, v2
	s_nop 1
	v_cndmask_b32_e64 v2, v2, v3, s[6:7]
	v_rsq_f32_e32 v2, v2
	s_nop 0
	v_mul_f32_e32 v3, 0x45800000, v2
	v_cndmask_b32_e64 v2, v2, v3, s[6:7]
	v_fmamk_f32 v132, v132, 0x3b800000, v188
	v_mul_f32_e32 v3, 0x4b800000, v132
	v_cmp_gt_f32_e64 s[6:7], s74, v132
	s_nop 1
	v_cndmask_b32_e64 v132, v132, v3, s[6:7]
	v_rsq_f32_e32 v132, v132
	s_nop 0
	v_mul_f32_e32 v3, 0x45800000, v132
	v_cndmask_b32_e64 v132, v132, v3, s[6:7]
	v_fmamk_f32 v134, v134, 0x3b800000, v188
	v_mul_f32_e32 v3, 0x4b800000, v134
	v_cmp_gt_f32_e64 s[6:7], s74, v134
	s_nop 1
	v_cndmask_b32_e64 v134, v134, v3, s[6:7]
	v_rsq_f32_e32 v134, v134
	s_nop 0
	v_mul_f32_e32 v3, 0x45800000, v134
	v_cndmask_b32_e64 v134, v134, v3, s[6:7]
	v_fmamk_f32 v138, v138, 0x3b800000, v188
	v_mul_f32_e32 v3, 0x4b800000, v138
	v_cmp_gt_f32_e64 s[6:7], s74, v138
	s_nop 1
	v_cndmask_b32_e64 v138, v138, v3, s[6:7]
	v_rsq_f32_e32 v138, v138
	s_nop 0
	v_mul_f32_e32 v3, 0x45800000, v138
	v_cndmask_b32_e64 v138, v138, v3, s[6:7]
	v_fmamk_f32 v140, v140, 0x3b800000, v188
	v_mul_f32_e32 v3, 0x4b800000, v140
	v_cmp_gt_f32_e64 s[6:7], s74, v140
	s_nop 1
	v_cndmask_b32_e64 v140, v140, v3, s[6:7]
	v_rsq_f32_e32 v140, v140
	s_nop 0
	v_mul_f32_e32 v3, 0x45800000, v140
	v_cndmask_b32_e64 v140, v140, v3, s[6:7]
	v_fmamk_f32 v142, v142, 0x3b800000, v188
	v_mul_f32_e32 v3, 0x4b800000, v142
	v_cmp_gt_f32_e64 s[6:7], s74, v142
	s_nop 1
	v_cndmask_b32_e64 v142, v142, v3, s[6:7]
	v_rsq_f32_e32 v142, v142
	s_nop 0
	v_mul_f32_e32 v3, 0x45800000, v142
	v_cndmask_b32_e64 v142, v142, v3, s[6:7]
	v_fmamk_f32 v136, v136, 0x3b800000, v188
	v_mul_f32_e32 v3, 0x4b800000, v136
	v_cmp_gt_f32_e64 s[6:7], s74, v136
	s_nop 1
	v_cndmask_b32_e64 v136, v136, v3, s[6:7]
	v_rsq_f32_e32 v136, v136
	s_nop 0
	v_mul_f32_e32 v3, 0x45800000, v136
	v_cndmask_b32_e64 v136, v136, v3, s[6:7]
	s_cmp_lg_u32 s39, 8
	s_cbranch_scc1 .LBB0_323
; template <int EPI>
; __device__ __forceinline__ void gemm_stream(const bf16_t* __restrict__ A, const bf16_t* __restrict__ Bt, int K, const TileWalk& tw,
;                                             const EpiArgs& ea, unsigned char* smem) {
;     ...
;                     const float rb = rsqrtf(ea.sq_b[tok] * (1.f / 256) + EPS);
;                     const float f = (kt == 8) ? rsqrtf(ea.sq_c[tok] * (1.f / 512) + EPS) / rb : rb;
; #pragma unroll
;                     for (int n = 0; n < 4; ++n) acc[m][n] *= f;
	v_fmamk_f32 v144, v144, 0x3b000000, v188
	v_mul_f32_e32 v3, 0x4b800000, v144
	v_cmp_gt_f32_e32 vcc, s74, v144
	s_nop 1
	v_cndmask_b32_e32 v144, v144, v3, vcc
	v_rsq_f32_e32 v144, v144
	s_nop 0
	v_mul_f32_e32 v3, 0x45800000, v144
	v_cndmask_b32_e32 v144, v144, v3, vcc
	v_div_scale_f32 v3, s[4:5], v0, v0, v144
	v_rcp_f32_e32 v152, v3
	v_div_scale_f32 v153, vcc, v144, v0, v144
	v_fma_f32 v154, -v3, v152, 1.0
	v_fmac_f32_e32 v152, v154, v152
	v_mul_f32_e32 v154, v153, v152
	v_fma_f32 v155, -v3, v154, v153
	v_fmac_f32_e32 v154, v155, v152
	v_fma_f32 v3, -v3, v154, v153
	v_div_fmas_f32 v3, v3, v152, v154
	v_div_fixup_f32 v0, v3, v0, v144
	v_fmamk_f32 v145, v145, 0x3b000000, v188
	v_mul_f32_e32 v3, 0x4b800000, v145
	v_cmp_gt_f32_e32 vcc, s74, v145
	s_nop 1
	v_cndmask_b32_e32 v145, v145, v3, vcc
	v_rsq_f32_e32 v145, v145
	s_nop 0
	v_mul_f32_e32 v3, 0x45800000, v145
	v_cndmask_b32_e32 v145, v145, v3, vcc
	v_div_scale_f32 v3, s[4:5], v2, v2, v145
	v_rcp_f32_e32 v152, v3
	v_div_scale_f32 v153, vcc, v145, v2, v145
	v_fma_f32 v154, -v3, v152, 1.0
	v_fmac_f32_e32 v152, v154, v152
	v_mul_f32_e32 v154, v153, v152
	v_fma_f32 v155, -v3, v154, v153
	v_fmac_f32_e32 v154, v155, v152
	v_fma_f32 v3, -v3, v154, v153
	v_div_fmas_f32 v3, v3, v152, v154
	v_div_fixup_f32 v2, v3, v2, v145
	v_fmamk_f32 v146, v146, 0x3b000000, v188
	v_mul_f32_e32 v3, 0x4b800000, v146
	v_cmp_gt_f32_e32 vcc, s74, v146
	s_nop 1
	v_cndmask_b32_e32 v146, v146, v3, vcc
	v_rsq_f32_e32 v146, v146
	s_nop 0
	v_mul_f32_e32 v3, 0x45800000, v146
	v_cndmask_b32_e32 v146, v146, v3, vcc
	v_div_scale_f32 v3, s[4:5], v132, v132, v146
	v_rcp_f32_e32 v152, v3
	v_div_scale_f32 v153, vcc, v146, v132, v146
	v_fma_f32 v154, -v3, v152, 1.0
	v_fmac_f32_e32 v152, v154, v152
	v_mul_f32_e32 v154, v153, v152
	v_fma_f32 v155, -v3, v154, v153
	v_fmac_f32_e32 v154, v155, v152
	v_fma_f32 v3, -v3, v154, v153
	v_div_fmas_f32 v3, v3, v152, v154
	v_div_fixup_f32 v132, v3, v132, v146
	v_fmamk_f32 v147, v147, 0x3b000000, v188
	v_mul_f32_e32 v3, 0x4b800000, v147
	v_cmp_gt_f32_e32 vcc, s74, v147
	s_nop 1
	v_cndmask_b32_e32 v147, v147, v3, vcc
	v_rsq_f32_e32 v147, v147
	s_nop 0
	v_mul_f32_e32 v3, 0x45800000, v147
	v_cndmask_b32_e32 v147, v147, v3, vcc
	v_div_scale_f32 v3, s[4:5], v134, v134, v147
	v_rcp_f32_e32 v152, v3
	v_div_scale_f32 v153, vcc, v147, v134, v147
	v_fma_f32 v154, -v3, v152, 1.0
	v_fmac_f32_e32 v152, v154, v152
	v_mul_f32_e32 v154, v153, v152
	v_fma_f32 v155, -v3, v154, v153
	v_fmac_f32_e32 v154, v155, v152
	v_fma_f32 v3, -v3, v154, v153
	v_div_fmas_f32 v3, v3, v152, v154
	v_div_fixup_f32 v134, v3, v134, v147
	v_fmamk_f32 v148, v148, 0x3b000000, v188
	v_mul_f32_e32 v3, 0x4b800000, v148
	v_cmp_gt_f32_e32 vcc, s74, v148
	s_nop 1
	v_cndmask_b32_e32 v148, v148, v3, vcc
	v_rsq_f32_e32 v148, v148
	s_nop 0
	v_mul_f32_e32 v3, 0x45800000, v148
	v_cndmask_b32_e32 v148, v148, v3, vcc
	v_div_scale_f32 v3, s[4:5], v138, v138, v148
	v_rcp_f32_e32 v152, v3
	v_div_scale_f32 v153, vcc, v148, v138, v148
	v_fma_f32 v154, -v3, v152, 1.0
	v_fmac_f32_e32 v152, v154, v152
	v_mul_f32_e32 v154, v153, v152
	v_fma_f32 v155, -v3, v154, v153
	v_fmac_f32_e32 v154, v155, v152
	v_fma_f32 v3, -v3, v154, v153
	v_div_fmas_f32 v3, v3, v152, v154
	v_div_fixup_f32 v138, v3, v138, v148
	v_fmamk_f32 v149, v149, 0x3b000000, v188
	v_mul_f32_e32 v3, 0x4b800000, v149
	v_cmp_gt_f32_e32 vcc, s74, v149
	s_nop 1
	v_cndmask_b32_e32 v149, v149, v3, vcc
	v_rsq_f32_e32 v149, v149
	s_nop 0
	v_mul_f32_e32 v3, 0x45800000, v149
	v_cndmask_b32_e32 v149, v149, v3, vcc
	v_div_scale_f32 v3, s[4:5], v140, v140, v149
	v_rcp_f32_e32 v152, v3
	v_div_scale_f32 v153, vcc, v149, v140, v149
	v_fma_f32 v154, -v3, v152, 1.0
	v_fmac_f32_e32 v152, v154, v152
	v_mul_f32_e32 v154, v153, v152
	v_fma_f32 v155, -v3, v154, v153
	v_fmac_f32_e32 v154, v155, v152
	v_fma_f32 v3, -v3, v154, v153
	v_div_fmas_f32 v3, v3, v152, v154
	v_div_fixup_f32 v140, v3, v140, v149
	v_fmamk_f32 v150, v150, 0x3b000000, v188
	v_mul_f32_e32 v3, 0x4b800000, v150
	v_cmp_gt_f32_e32 vcc, s74, v150
	s_nop 1
	v_cndmask_b32_e32 v150, v150, v3, vcc
	v_rsq_f32_e32 v150, v150
	s_nop 0
	v_mul_f32_e32 v3, 0x45800000, v150
	v_cndmask_b32_e32 v150, v150, v3, vcc
	v_div_scale_f32 v3, s[4:5], v142, v142, v150
	v_rcp_f32_e32 v152, v3
	v_div_scale_f32 v153, vcc, v150, v142, v150
	v_fma_f32 v154, -v3, v152, 1.0
	v_fmac_f32_e32 v152, v154, v152
	v_mul_f32_e32 v154, v153, v152
	v_fma_f32 v155, -v3, v154, v153
	v_fmac_f32_e32 v154, v155, v152
	v_fma_f32 v3, -v3, v154, v153
	v_div_fmas_f32 v3, v3, v152, v154
	v_div_fixup_f32 v142, v3, v142, v150
	v_fmamk_f32 v151, v151, 0x3b000000, v188
	v_mul_f32_e32 v3, 0x4b800000, v151
	v_cmp_gt_f32_e32 vcc, s74, v151
	s_nop 1
	v_cndmask_b32_e32 v151, v151, v3, vcc
	v_rsq_f32_e32 v151, v151
	s_nop 0
	v_mul_f32_e32 v3, 0x45800000, v151
	v_cndmask_b32_e32 v151, v151, v3, vcc
	v_div_scale_f32 v3, s[4:5], v136, v136, v151
	v_rcp_f32_e32 v152, v3
	v_div_scale_f32 v153, vcc, v151, v136, v151
	v_fma_f32 v154, -v3, v152, 1.0
	v_fmac_f32_e32 v152, v154, v152
	v_mul_f32_e32 v154, v153, v152
	v_fma_f32 v155, -v3, v154, v153
	v_fmac_f32_e32 v154, v155, v152
	v_fma_f32 v3, -v3, v154, v153
	v_div_fmas_f32 v3, v3, v152, v154
	v_div_fixup_f32 v136, v3, v136, v151
